# attention P.V: V reads of the first MFMA group issued inside the Q.K tail as soon as their registers are free (both steps)
# speedup vs baseline: 1.0116x; 1.0116x over previous
.LBB0_963:
	s_add_u32 s36, s28, s30
	s_addc_u32 s37, s29, s31
	s_add_u32 s34, s36, 0x100000
	s_addc_u32 s35, s37, 0
	s_lshl_b32 s9, s19, 14
	s_add_i32 s48, s95, s9
	s_mov_b32 m0, s48
	s_nop 0
	global_load_lds_dwordx4 v228, s[34:35]
	s_add_i32 m0, s48, 0x400
	s_nop 0
	global_load_lds_dwordx4 v231, s[34:35]
	ds_read_b128 v[236:239], v196 offset:12288
	s_waitcnt lgkmcnt(3)
	v_mfma_f32_16x16x32_bf16 v[120:123], v[184:187], v[36:39], v[120:123]
	v_exp_f32_e32 v196, v132
	v_exp_f32_e32 v208, v133
	v_add_f32_e32 v206, v152, v206
	v_add_f32_e32 v207, v136, v207
	v_mfma_f32_16x16x32_bf16 v[124:127], v[184:187], v[0:3], v[124:127]
	v_add_u32_e32 v209, s25, v233
	ds_read_b128 v[184:187], v209
	v_exp_f32_e32 v210, v134
	v_exp_f32_e32 v211, v135
	s_waitcnt lgkmcnt(3)
	v_mfma_f32_16x16x32_bf16 v[132:135], v[176:179], v[0:3], v[148:151]
	v_mfma_f32_16x16x32_bf16 v[160:163], v[176:179], v[36:39], v[160:163]
	s_nop 1
	v_add_f32_e32 v148, v153, v206
	v_add_f32_e32 v149, v137, v207
	ds_read_b128 v[176:179], v209 offset:4096
	s_waitcnt lgkmcnt(3)
	v_mfma_f32_16x16x32_bf16 v[164:167], v[180:183], v[0:3], v[164:167]
	v_exp_f32_e32 v212, v128
	v_exp_f32_e32 v213, v129
	v_add_f32_e32 v148, v154, v148
	v_mfma_f32_16x16x32_bf16 v[168:171], v[180:183], v[36:39], v[168:171]
	v_add_f32_e32 v149, v138, v149
	ds_read_b128 v[180:183], v209 offset:8192
	v_exp_f32_e32 v219, v130
	v_exp_f32_e32 v235, v131
	s_waitcnt lgkmcnt(3)
	v_mfma_f32_16x16x32_bf16 v[128:131], v[236:239], v[0:3], v[140:143]
	v_add_f32_e32 v148, v155, v148
	v_add_f32_e32 v149, v139, v149
	v_mfma_f32_16x16x32_bf16 v[140:143], v[236:239], v[36:39], v[172:175]
	s_nop 2
	ds_read_b128 v[172:175], v209 offset:12288
	s_waitcnt lgkmcnt(3)
	v_mfma_f32_16x16x32_bf16 v[120:123], v[184:187], v[28:31], v[120:123]
	v_add_f32_e32 v150, v188, v148
	v_add_f32_e32 v149, v190, v149
	v_mfma_f32_16x16x32_bf16 v[124:127], v[184:187], v[12:15], v[124:127]
	v_cvt_pk_bf16_f32 v148, v156, v157
	v_add_u32_e32 v206, s25, v230
	ds_read_b128 v[184:187], v206
	v_add_f32_e32 v150, v189, v150
	v_add_f32_e32 v151, v191, v149
	s_waitcnt lgkmcnt(3)
	v_mfma_f32_16x16x32_bf16 v[132:135], v[176:179], v[12:15], v[132:135]
	v_cvt_pk_bf16_f32 v149, v158, v159
	v_mfma_f32_16x16x32_bf16 v[156:159], v[176:179], v[28:31], v[160:163]
	ds_read_b128 v[176:179], v206 offset:4096
	s_waitcnt lgkmcnt(3)
	v_mfma_f32_16x16x32_bf16 v[162:165], v[180:183], v[12:15], v[164:167]
	s_nop 0
	v_add_f32_e32 v160, v194, v150
	v_add_f32_e32 v151, v192, v151
	v_mfma_f32_16x16x32_bf16 v[166:169], v[180:183], v[28:31], v[168:171]
	v_cvt_pk_bf16_f32 v150, v152, v153
	ds_read_b128 v[180:183], v206 offset:8192
	s_waitcnt lgkmcnt(3)
	v_mfma_f32_16x16x32_bf16 v[128:131], v[172:175], v[12:15], v[128:131]
	v_add_f32_e32 v160, v195, v160
	v_add_f32_e32 v161, v193, v151
	v_mfma_f32_16x16x32_bf16 v[140:143], v[172:175], v[28:31], v[140:143]
	v_cvt_pk_bf16_f32 v151, v154, v155
	ds_read_b128 v[152:155], v206 offset:12288
	s_waitcnt lgkmcnt(3)
	v_mfma_f32_16x16x32_bf16 v[120:123], v[184:187], v[24:27], v[120:123]
	v_add_f32_e32 v174, v196, v160
	v_add_f32_e32 v161, v212, v161
	v_mfma_f32_16x16x32_bf16 v[124:127], v[184:187], v[8:11], v[124:127]
	v_cvt_pk_bf16_f32 v160, v144, v145
	v_add_u32_e32 v186, s25, v226
	ds_read_b128 v[170:173], v186 offset:16384
	v_add_f32_e32 v184, v208, v174
	v_add_f32_e32 v185, v213, v161
	s_waitcnt lgkmcnt(3)
	v_mfma_f32_16x16x32_bf16 v[132:135], v[176:179], v[8:11], v[132:135]
	v_cvt_pk_bf16_f32 v161, v146, v147
	v_mfma_f32_16x16x32_bf16 v[144:147], v[176:179], v[24:27], v[156:159]
	s_nop 2
	ds_read_b128 v[156:159], v186 offset:18432
	s_waitcnt lgkmcnt(3)
	v_mfma_f32_16x16x32_bf16 v[174:177], v[180:183], v[8:11], v[162:165]
	v_mfma_f32_16x16x32_bf16 v[178:181], v[180:183], v[24:27], v[166:169]
	s_nop 1
	v_add_f32_e32 v163, v210, v184
	v_add_f32_e32 v164, v219, v185
	v_cvt_pk_bf16_f32 v162, v136, v137
	ds_read_b128 v[182:185], v186 offset:20480
	v_add_f32_e32 v206, v211, v163
	v_add_f32_e32 v207, v235, v164
	s_waitcnt lgkmcnt(3)
	v_mfma_f32_16x16x32_bf16 v[128:131], v[152:155], v[8:11], v[128:131]
	v_cvt_pk_bf16_f32 v163, v138, v139
	v_mfma_f32_16x16x32_bf16 v[136:139], v[152:155], v[24:27], v[140:143]
	s_nop 2
	ds_read_b128 v[140:143], v186 offset:22528
	s_waitcnt lgkmcnt(3)
	v_mfma_f32_16x16x32_bf16 v[120:123], v[170:173], v[32:35], v[120:123]
	v_cvt_pk_bf16_f32 v164, v188, v189
	v_mfma_f32_16x16x32_bf16 v[124:127], v[170:173], v[16:19], v[124:127]
	v_add_u32_e32 v152, s25, v224
	ds_read_b128 v[168:171], v152 offset:16384
	s_waitcnt lgkmcnt(3)
	v_mfma_f32_16x16x32_bf16 v[132:135], v[156:159], v[16:19], v[132:135]
	v_cvt_pk_bf16_f32 v165, v194, v195
	v_mfma_f32_16x16x32_bf16 v[186:189], v[156:159], v[32:35], v[144:147]
	ds_read_b128 v[236:239], v152 offset:18432
	s_waitcnt lgkmcnt(3)
	v_mfma_f32_16x16x32_bf16 v[240:243], v[182:185], v[16:19], v[174:177]
	v_cvt_pk_bf16_f32 v166, v196, v208
	v_mfma_f32_16x16x32_bf16 v[176:179], v[182:185], v[32:35], v[178:181]
	s_nop 2
	ds_read_b128 v[180:183], v152 offset:20480
	s_waitcnt lgkmcnt(3)
	v_mfma_f32_16x16x32_bf16 v[128:131], v[140:143], v[16:19], v[128:131]
	v_cvt_pk_bf16_f32 v167, v210, v211
	v_mfma_f32_16x16x32_bf16 v[244:247], v[140:143], v[32:35], v[136:139]
	ds_read_b128 v[248:251], v152 offset:22528
	s_waitcnt lgkmcnt(3)
	v_mfma_f32_16x16x32_bf16 v[152:155], v[168:171], v[20:23], v[124:127]
	v_mfma_f32_16x16x32_bf16 v[144:147], v[168:171], v[44:47], v[120:123]
	v_cvt_pk_bf16_f32 v168, v190, v191
	s_waitcnt lgkmcnt(2)
	v_mfma_f32_16x16x32_bf16 v[156:159], v[236:239], v[20:23], v[132:135]
	v_cvt_pk_bf16_f32 v169, v192, v193
	v_mfma_f32_16x16x32_bf16 v[172:175], v[236:239], v[44:47], v[186:189]
	s_lshl_b32 s34, s8, 14
	s_add_i32 s48, s34, 0
	s_add_i32 s48, s48, 0x12000
	v_add_u32_e32 v253, s48, v223
	ds_read_b64_tr_b16 v[184:185], v253 offset:8192
	ds_read_b64_tr_b16 v[186:187], v253 offset:12288
	s_waitcnt lgkmcnt(3)
	v_mfma_f32_16x16x32_bf16 v[140:143], v[180:183], v[20:23], v[240:243]
	v_cvt_pk_bf16_f32 v170, v212, v213
	v_mfma_f32_16x16x32_bf16 v[136:139], v[180:183], v[44:47], v[176:179]
	s_nop 2
	ds_read_b64_tr_b16 v[176:177], v253
	ds_read_b64_tr_b16 v[178:179], v253 offset:4096
	s_waitcnt lgkmcnt(4)
	v_mfma_f32_16x16x32_bf16 v[132:135], v[248:251], v[20:23], v[128:131]
	v_cvt_pk_bf16_f32 v171, v219, v235
	v_mfma_f32_16x16x32_bf16 v[128:131], v[248:251], v[44:47], v[244:247]
	v_add_u32_e32 v196, s48, v222
	v_add_u32_e32 v219, s48, v223
	ds_read_b64_tr_b16 v[120:121], v196
	ds_read_b64_tr_b16 v[122:123], v196 offset:4096
	ds_read_b64_tr_b16 v[124:125], v196 offset:8192
	ds_read_b64_tr_b16 v[126:127], v196 offset:12288
	ds_read_b64_tr_b16 v[182:183], v219 offset:4608
	ds_read_b64_tr_b16 v[180:181], v219 offset:512
	ds_read_b64_tr_b16 v[190:191], v219 offset:12800
	ds_read_b64_tr_b16 v[188:189], v219 offset:8704
	s_waitcnt lgkmcnt(10)
	v_mfma_f32_16x16x32_bf16 v[112:115], v[184:187], v[164:167], v[112:115]
	v_mfma_f32_16x16x32_bf16 v[116:119], v[184:187], v[168:171], v[116:119]
	v_max_f32_e32 v252, v152, v153
	s_waitcnt lgkmcnt(8)
	v_mfma_f32_16x16x32_bf16 v[112:115], v[176:179], v[148:151], v[112:115]
	v_max3_f32 v252, v252, v154, v155
	v_max3_f32 v252, v252, v156, v157
	v_max3_f32 v208, v252, v158, v159
	v_mfma_f32_16x16x32_bf16 v[116:119], v[176:179], v[160:163], v[116:119]
	ds_read_b64_tr_b16 v[192:193], v196 offset:512
	ds_read_b64_tr_b16 v[194:195], v196 offset:4608
	ds_read_b64_tr_b16 v[236:237], v196 offset:8704
	ds_read_b64_tr_b16 v[238:239], v196 offset:12800
	s_waitcnt lgkmcnt(10)
	v_mfma_f32_16x16x32_bf16 v[108:111], v[120:123], v[148:151], v[108:111]
	v_mfma_f32_16x16x32_bf16 v[176:179], v[120:123], v[160:163], v[104:107]
	s_waitcnt lgkmcnt(8)
	v_mfma_f32_16x16x32_bf16 v[104:107], v[124:127], v[164:167], v[108:111]
	s_nop 5
	v_max3_f32 v108, v208, v140, v141
	v_max3_f32 v108, v108, v142, v143
	v_max3_f32 v108, v108, v132, v133
	v_max3_f32 v120, v108, v134, v135
	v_mfma_f32_16x16x32_bf16 v[108:111], v[124:127], v[168:171], v[176:179]
	ds_read_b64_tr_b16 v[184:185], v219 offset:1024
	ds_read_b64_tr_b16 v[186:187], v219 offset:5120
	s_nop 0
	ds_read_b64_tr_b16 v[176:177], v219 offset:9216
	ds_read_b64_tr_b16 v[178:179], v219 offset:13312
	s_waitcnt lgkmcnt(10)
	v_mfma_f32_16x16x32_bf16 v[96:99], v[180:183], v[148:151], v[96:99]
	v_max_f32_e32 v121, v144, v145
	s_waitcnt lgkmcnt(8)
	v_mfma_f32_16x16x32_bf16 v[96:99], v[188:191], v[164:167], v[96:99]
	v_max3_f32 v121, v121, v146, v147
	v_max3_f32 v121, v121, v172, v173
	v_max3_f32 v121, v121, v174, v175
	v_mfma_f32_16x16x32_bf16 v[100:103], v[180:183], v[160:163], v[100:103]
	v_mfma_f32_16x16x32_bf16 v[100:103], v[188:191], v[168:171], v[100:103]
	ds_read_b64_tr_b16 v[188:189], v196 offset:1024
	ds_read_b64_tr_b16 v[190:191], v196 offset:5120
	ds_read_b64_tr_b16 v[180:181], v196 offset:9216
	ds_read_b64_tr_b16 v[182:183], v196 offset:13312
	s_waitcnt lgkmcnt(10)
	v_mfma_f32_16x16x32_bf16 v[92:95], v[192:195], v[148:151], v[92:95]
	v_mfma_f32_16x16x32_bf16 v[122:125], v[192:195], v[160:163], v[88:91]
	s_waitcnt lgkmcnt(8)
	v_mfma_f32_16x16x32_bf16 v[88:91], v[236:239], v[164:167], v[92:95]
	s_nop 5
	v_max3_f32 v92, v121, v136, v137
	v_max3_f32 v92, v92, v138, v139
	v_max3_f32 v92, v92, v128, v129
	v_max3_f32 v121, v92, v130, v131
	v_mfma_f32_16x16x32_bf16 v[92:95], v[236:239], v[168:171], v[122:125]
	s_nop 2
	v_max_f32_e32 v122, v120, v121
	v_cmp_ge_f32_e32 vcc, s62, v122
	s_cmp_lg_u64 vcc, exec
	s_cselect_b64 s[34:35], -1, 0
	s_cmp_eq_u64 vcc, exec
	s_cbranch_scc1 .LBB0_965
	ds_bpermute_b32 v48, v220, v120
	v_max_f32_e32 v49, v120, v120
	v_max_f32_e32 v50, v121, v121
	s_waitcnt lgkmcnt(0)
	v_max_f32_e32 v48, v48, v48
	v_max_f32_e32 v48, v49, v48
	ds_bpermute_b32 v49, v221, v48
	s_waitcnt lgkmcnt(0)
	v_max3_f32 v48, v48, v49, 0
	ds_bpermute_b32 v49, v220, v121
	v_exp_f32_e64 v208, -v48
	v_sub_f32_e32 v152, v152, v48
	v_sub_f32_e32 v153, v153, v48
	v_sub_f32_e32 v154, v154, v48
	s_waitcnt lgkmcnt(0)
	v_max_f32_e32 v49, v49, v49
	v_max_f32_e32 v49, v50, v49
	ds_bpermute_b32 v50, v221, v49
	v_sub_f32_e32 v155, v155, v48
	v_sub_f32_e32 v156, v156, v48
	v_sub_f32_e32 v157, v157, v48
	v_sub_f32_e32 v158, v158, v48
	s_waitcnt lgkmcnt(0)
	v_max3_f32 v49, v49, v50, 0
	v_exp_f32_e64 v209, -v49
	v_pk_add_f32 v[202:203], v[202:203], v[48:49]
	v_sub_f32_e32 v159, v159, v48
	v_pk_add_f32 v[120:121], v[202:203], 0 neg_lo:[1,1] neg_hi:[1,1]
	v_xor_b32_e32 v124, 0x80000000, v203
	v_sub_f32_e32 v143, v143, v48
	v_sub_f32_e32 v142, v142, v48
	v_sub_f32_e32 v141, v141, v48
	v_sub_f32_e32 v140, v140, v48
	v_sub_f32_e32 v135, v135, v48
	v_sub_f32_e32 v134, v134, v48
	v_sub_f32_e32 v133, v133, v48
	v_sub_f32_e32 v132, v132, v48
	v_mov_b32_e32 v121, v120
	v_mov_b32_e32 v122, v120
	v_mov_b32_e32 v123, v120
	v_sub_f32_e32 v144, v144, v49
	v_sub_f32_e32 v145, v145, v49
	v_sub_f32_e32 v146, v146, v49
	v_sub_f32_e32 v147, v147, v49
	v_sub_f32_e32 v172, v172, v49
	v_sub_f32_e32 v173, v173, v49
	v_sub_f32_e32 v174, v174, v49
	v_sub_f32_e32 v175, v175, v49
	v_sub_f32_e32 v139, v139, v49
	v_sub_f32_e32 v138, v138, v49
	v_sub_f32_e32 v137, v137, v49
	v_sub_f32_e32 v136, v136, v49
	v_sub_f32_e32 v131, v131, v49
	v_sub_f32_e32 v130, v130, v49
	v_sub_f32_e32 v129, v129, v49
	v_sub_f32_e32 v128, v128, v49
	v_mov_b32_e32 v125, v124
	v_mov_b32_e32 v126, v124
	v_mov_b32_e32 v127, v124
	v_mov_b32_e32 v48, v120
	v_mov_b32_e32 v49, v120
	v_mov_b32_e32 v50, v120
	v_mov_b32_e32 v51, v120
	v_mov_b32_e32 v52, v124
	v_mov_b32_e32 v53, v124
	v_mov_b32_e32 v54, v124
	v_mov_b32_e32 v55, v124
	s_branch .LBB0_966

.LBB0_971:
	s_add_u32 s36, s36, 0x180000
	s_addc_u32 s37, s37, 0
	s_add_i32 s25, s48, s77
	s_mov_b32 m0, s25
	s_nop 0
	global_load_lds_dwordx4 v228, s[36:37]
	s_add_i32 m0, s25, 0x400
	s_nop 0
	global_load_lds_dwordx4 v231, s[36:37]
	ds_read_b128 v[246:249], v243 offset:12288
	s_waitcnt lgkmcnt(3)
	v_mfma_f32_16x16x32_bf16 v[164:167], v[192:195], v[0:3], v[164:167]
	v_exp_f32_e32 v210, v132
	v_exp_f32_e32 v211, v133
	v_add_f32_e32 v212, v156, v245
	v_mfma_f32_16x16x32_bf16 v[160:163], v[192:195], v[36:39], v[160:163]
	v_add_f32_e32 v213, v148, v244
	v_add_u32_e32 v243, s49, v233
	ds_read_b128 v[192:195], v243
	v_exp_f32_e32 v250, v134
	v_exp_f32_e32 v251, v135
	s_waitcnt lgkmcnt(3)
	v_mfma_f32_16x16x32_bf16 v[132:135], v[188:191], v[0:3], v[180:183]
	v_add_f32_e32 v212, v157, v212
	v_add_f32_e32 v213, v149, v213
	v_mfma_f32_16x16x32_bf16 v[172:175], v[188:191], v[36:39], v[172:175]
	ds_read_b128 v[180:183], v243 offset:4096
	s_waitcnt lgkmcnt(3)
	v_mfma_f32_16x16x32_bf16 v[176:179], v[184:187], v[0:3], v[176:179]
	v_exp_f32_e32 v215, v128
	v_exp_f32_e32 v214, v129
	v_add_f32_e32 v188, v158, v212
	v_mfma_f32_16x16x32_bf16 v[140:143], v[184:187], v[36:39], v[140:143]
	v_add_f32_e32 v189, v150, v213
	ds_read_b128 v[184:187], v243 offset:8192
	v_exp_f32_e32 v218, v130
	v_exp_f32_e32 v198, v131
	s_waitcnt lgkmcnt(3)
	v_mfma_f32_16x16x32_bf16 v[128:131], v[246:249], v[0:3], v[168:171]
	v_add_f32_e32 v199, v159, v188
	v_add_f32_e32 v212, v151, v189
	v_mfma_f32_16x16x32_bf16 v[168:171], v[246:249], v[36:39], v[136:139]
	ds_read_b128 v[188:191], v243 offset:12288
	s_waitcnt lgkmcnt(3)
	v_mfma_f32_16x16x32_bf16 v[164:167], v[192:195], v[12:15], v[164:167]
	v_add_f32_e32 v137, v235, v199
	v_add_f32_e32 v138, v237, v212
	v_mfma_f32_16x16x32_bf16 v[160:163], v[192:195], v[28:31], v[160:163]
	v_cvt_pk_bf16_f32 v136, v152, v153
	v_add_u32_e32 v199, s49, v230
	ds_read_b128 v[192:195], v199
	v_add_f32_e32 v139, v236, v137
	v_add_f32_e32 v138, v238, v138
	s_waitcnt lgkmcnt(3)
	v_mfma_f32_16x16x32_bf16 v[132:135], v[180:183], v[12:15], v[132:135]
	v_cvt_pk_bf16_f32 v137, v154, v155
	v_mfma_f32_16x16x32_bf16 v[152:155], v[180:183], v[28:31], v[172:175]
	s_nop 2
	ds_read_b128 v[172:175], v199 offset:4096
	s_waitcnt lgkmcnt(3)
	v_mfma_f32_16x16x32_bf16 v[176:179], v[184:187], v[12:15], v[176:179]
	v_add_f32_e32 v139, v241, v139
	v_add_f32_e32 v212, v239, v138
	v_mfma_f32_16x16x32_bf16 v[140:143], v[184:187], v[28:31], v[140:143]
	v_cvt_pk_bf16_f32 v138, v156, v157
	ds_read_b128 v[180:183], v199 offset:8192
	v_add_f32_e32 v213, v242, v139
	v_add_f32_e32 v212, v240, v212
	s_waitcnt lgkmcnt(3)
	v_mfma_f32_16x16x32_bf16 v[128:131], v[188:191], v[12:15], v[128:131]
	v_cvt_pk_bf16_f32 v139, v158, v159
	v_mfma_f32_16x16x32_bf16 v[156:159], v[188:191], v[28:31], v[168:171]
	s_nop 2
	ds_read_b128 v[168:171], v199 offset:12288
	s_waitcnt lgkmcnt(3)
	v_mfma_f32_16x16x32_bf16 v[164:167], v[192:195], v[8:11], v[164:167]
	v_mfma_f32_16x16x32_bf16 v[184:187], v[192:195], v[24:27], v[160:163]
	s_nop 2
	v_add_f32_e32 v161, v210, v213
	v_add_f32_e32 v162, v215, v212
	v_cvt_pk_bf16_f32 v160, v144, v145
	v_add_u32_e32 v192, s49, v226
	ds_read_b128 v[188:191], v192 offset:16384
	v_add_f32_e32 v163, v211, v161
	v_add_f32_e32 v162, v214, v162
	s_waitcnt lgkmcnt(3)
	v_mfma_f32_16x16x32_bf16 v[132:135], v[172:175], v[8:11], v[132:135]
	v_cvt_pk_bf16_f32 v161, v146, v147
	v_mfma_f32_16x16x32_bf16 v[144:147], v[172:175], v[24:27], v[152:155]
	s_nop 2
	ds_read_b128 v[152:155], v192 offset:18432
	s_waitcnt lgkmcnt(3)
	v_mfma_f32_16x16x32_bf16 v[172:175], v[180:183], v[8:11], v[176:179]
	v_add_f32_e32 v163, v250, v163
	v_add_f32_e32 v193, v218, v162
	v_mfma_f32_16x16x32_bf16 v[140:143], v[180:183], v[24:27], v[140:143]
	v_cvt_pk_bf16_f32 v162, v148, v149
	ds_read_b128 v[176:179], v192 offset:20480
	v_add_f32_e32 v194, v251, v163
	v_add_f32_e32 v195, v198, v193
	s_waitcnt lgkmcnt(3)
	v_mfma_f32_16x16x32_bf16 v[128:131], v[168:171], v[8:11], v[128:131]
	v_cvt_pk_bf16_f32 v163, v150, v151
	v_mfma_f32_16x16x32_bf16 v[148:151], v[168:171], v[24:27], v[156:159]
	s_nop 2
	ds_read_b128 v[156:159], v192 offset:22528
	s_waitcnt lgkmcnt(3)
	v_mfma_f32_16x16x32_bf16 v[168:171], v[188:191], v[16:19], v[164:167]
	v_cvt_pk_bf16_f32 v164, v235, v236
	v_mfma_f32_16x16x32_bf16 v[180:183], v[188:191], v[32:35], v[184:187]
	v_add_u32_e32 v192, s49, v224
	s_nop 1
	ds_read_b128 v[184:187], v192 offset:16384
	s_waitcnt lgkmcnt(3)
	v_mfma_f32_16x16x32_bf16 v[132:135], v[152:155], v[16:19], v[132:135]
	v_cvt_pk_bf16_f32 v165, v241, v242
	v_mfma_f32_16x16x32_bf16 v[188:191], v[152:155], v[32:35], v[144:147]
	ds_read_b128 v[242:245], v192 offset:18432
	s_waitcnt lgkmcnt(3)
	v_mfma_f32_16x16x32_bf16 v[140:143], v[176:179], v[32:35], v[140:143]
	v_cvt_pk_bf16_f32 v166, v210, v211
	v_mfma_f32_16x16x32_bf16 v[246:249], v[176:179], v[16:19], v[172:175]
	ds_read_b128 v[176:179], v192 offset:20480
	s_waitcnt lgkmcnt(3)
	v_mfma_f32_16x16x32_bf16 v[128:131], v[156:159], v[16:19], v[128:131]
	v_cvt_pk_bf16_f32 v167, v250, v251
	v_mfma_f32_16x16x32_bf16 v[250:253], v[156:159], v[32:35], v[148:151]
	ds_read_b128 v[210:213], v192 offset:22528
	s_waitcnt lgkmcnt(3)
	v_mfma_f32_16x16x32_bf16 v[156:159], v[184:187], v[20:23], v[168:171]
	v_cvt_pk_bf16_f32 v168, v237, v238
	v_mfma_f32_16x16x32_bf16 v[144:147], v[184:187], v[44:47], v[180:183]
	s_lshl_b32 s25, s5, 14
	s_add_i32 s25, s25, 0
	s_add_i32 s25, s25, 0x12000
	v_add_u32_e32 v199, s25, v223
	ds_read_b64_tr_b16 v[184:185], v199
	ds_read_b64_tr_b16 v[186:187], v199 offset:4096
	s_waitcnt lgkmcnt(4)
	v_mfma_f32_16x16x32_bf16 v[152:155], v[242:245], v[20:23], v[132:135]
	v_cvt_pk_bf16_f32 v169, v239, v240
	v_mfma_f32_16x16x32_bf16 v[172:175], v[242:245], v[44:47], v[188:191]
	s_waitcnt lgkmcnt(3)
	v_mfma_f32_16x16x32_bf16 v[148:151], v[176:179], v[20:23], v[246:249]
	v_cvt_pk_bf16_f32 v170, v215, v214
	v_mfma_f32_16x16x32_bf16 v[140:143], v[176:179], v[44:47], v[140:143]
	s_waitcnt lgkmcnt(2)
	v_mfma_f32_16x16x32_bf16 v[132:135], v[210:213], v[20:23], v[128:131]
	v_cvt_pk_bf16_f32 v171, v218, v198
	v_mfma_f32_16x16x32_bf16 v[128:131], v[210:213], v[44:47], v[250:253]
	v_add_u32_e32 v235, s25, v222
	v_add_u32_e32 v236, s25, v223
	ds_read_b64_tr_b16 v[210:211], v236 offset:8192
	ds_read_b64_tr_b16 v[212:213], v236 offset:12288
	ds_read_b64_tr_b16 v[176:177], v235
	ds_read_b64_tr_b16 v[178:179], v235 offset:4096
	ds_read_b64_tr_b16 v[180:181], v235 offset:8192
	ds_read_b64_tr_b16 v[182:183], v235 offset:12288
	ds_read_b64_tr_b16 v[190:191], v236 offset:4608
	ds_read_b64_tr_b16 v[188:189], v236 offset:512
	ds_read_b64_tr_b16 v[240:241], v236 offset:12800
	ds_read_b64_tr_b16 v[238:239], v236 offset:8704
	s_waitcnt lgkmcnt(10)
	v_mfma_f32_16x16x32_bf16 v[112:115], v[184:187], v[136:139], v[112:115]
	v_mfma_f32_16x16x32_bf16 v[116:119], v[184:187], v[160:163], v[116:119]
	v_max_f32_e32 v184, v156, v157
	s_waitcnt lgkmcnt(8)
	v_mfma_f32_16x16x32_bf16 v[112:115], v[210:213], v[164:167], v[112:115]
	v_max3_f32 v184, v184, v158, v159
	v_max3_f32 v184, v184, v152, v153
	v_max3_f32 v184, v184, v154, v155
	v_mfma_f32_16x16x32_bf16 v[116:119], v[210:213], v[168:171], v[116:119]
	ds_read_b64_tr_b16 v[210:211], v235 offset:512
	ds_read_b64_tr_b16 v[212:213], v235 offset:4608
	ds_read_b64_tr_b16 v[242:243], v235 offset:8704
	ds_read_b64_tr_b16 v[244:245], v235 offset:12800
	s_waitcnt lgkmcnt(10)
	v_mfma_f32_16x16x32_bf16 v[104:107], v[176:179], v[136:139], v[104:107]
	v_mfma_f32_16x16x32_bf16 v[176:179], v[176:179], v[160:163], v[108:111]
	s_waitcnt lgkmcnt(8)
	v_mfma_f32_16x16x32_bf16 v[108:111], v[180:183], v[164:167], v[104:107]
	s_nop 5
	v_max3_f32 v104, v184, v148, v149
	v_max3_f32 v104, v104, v150, v151
	v_max3_f32 v104, v104, v132, v133
	v_max3_f32 v193, v104, v134, v135
	v_mfma_f32_16x16x32_bf16 v[104:107], v[180:183], v[168:171], v[176:179]
	ds_read_b64_tr_b16 v[184:185], v236 offset:1024
	ds_read_b64_tr_b16 v[186:187], v236 offset:5120
	s_nop 0
	ds_read_b64_tr_b16 v[176:177], v236 offset:9216
	ds_read_b64_tr_b16 v[178:179], v236 offset:13312
	s_waitcnt lgkmcnt(10)
	v_mfma_f32_16x16x32_bf16 v[96:99], v[188:191], v[136:139], v[96:99]
	v_max_f32_e32 v180, v144, v145
	s_waitcnt lgkmcnt(8)
	v_mfma_f32_16x16x32_bf16 v[96:99], v[238:241], v[164:167], v[96:99]
	v_max3_f32 v180, v180, v146, v147
	v_max3_f32 v180, v180, v172, v173
	v_max3_f32 v192, v180, v174, v175
	v_mfma_f32_16x16x32_bf16 v[100:103], v[188:191], v[160:163], v[100:103]
	v_mfma_f32_16x16x32_bf16 v[100:103], v[238:241], v[168:171], v[100:103]
	ds_read_b64_tr_b16 v[188:189], v235 offset:1024
	ds_read_b64_tr_b16 v[190:191], v235 offset:5120
	ds_read_b64_tr_b16 v[180:181], v235 offset:9216
	ds_read_b64_tr_b16 v[182:183], v235 offset:13312
	s_waitcnt lgkmcnt(10)
	v_mfma_f32_16x16x32_bf16 v[88:91], v[210:213], v[136:139], v[88:91]
	v_mfma_f32_16x16x32_bf16 v[210:213], v[210:213], v[160:163], v[92:95]
	s_waitcnt lgkmcnt(8)
	v_mfma_f32_16x16x32_bf16 v[92:95], v[242:245], v[164:167], v[88:91]
	s_nop 5
	v_max3_f32 v88, v192, v140, v141
	v_max3_f32 v88, v88, v142, v143
	v_max3_f32 v88, v88, v128, v129
	v_max3_f32 v237, v88, v130, v131
	v_mfma_f32_16x16x32_bf16 v[88:91], v[242:245], v[168:171], v[210:213]
	v_max_f32_e32 v192, v193, v237
	v_cmp_ge_f32_e32 vcc, s62, v192
	s_cmp_lg_u64 vcc, exec
	s_cselect_b64 s[36:37], -1, 0
	s_cmp_eq_u64 vcc, exec
	v_mov_b32_e32 v192, 1.0
	s_cbranch_scc1 .LBB0_973
	ds_bpermute_b32 v48, v220, v193
	v_max_f32_e32 v49, v193, v193
	v_max_f32_e32 v50, v237, v237
	s_waitcnt lgkmcnt(0)
	v_max_f32_e32 v48, v48, v48
	v_max_f32_e32 v48, v49, v48
	ds_bpermute_b32 v49, v221, v48
	s_waitcnt lgkmcnt(0)
	v_max3_f32 v48, v48, v49, 0
	ds_bpermute_b32 v49, v220, v237
	v_exp_f32_e64 v192, -v48
	v_sub_f32_e32 v156, v156, v48
	v_sub_f32_e32 v157, v157, v48
	v_sub_f32_e32 v158, v158, v48
	s_waitcnt lgkmcnt(0)
	v_max_f32_e32 v49, v49, v49
	v_max_f32_e32 v49, v50, v49
	ds_bpermute_b32 v50, v221, v49
	v_sub_f32_e32 v159, v159, v48
	v_sub_f32_e32 v152, v152, v48
	v_sub_f32_e32 v153, v153, v48
	v_sub_f32_e32 v154, v154, v48
	s_waitcnt lgkmcnt(0)
	v_max3_f32 v49, v49, v50, 0
	v_exp_f32_e64 v193, -v49
	v_pk_add_f32 v[202:203], v[202:203], v[48:49]
	v_sub_f32_e32 v155, v155, v48
	v_pk_add_f32 v[120:121], v[202:203], 0 neg_lo:[1,1] neg_hi:[1,1]
	v_xor_b32_e32 v124, 0x80000000, v203
	v_sub_f32_e32 v151, v151, v48
	v_sub_f32_e32 v150, v150, v48
	v_sub_f32_e32 v149, v149, v48
	v_sub_f32_e32 v148, v148, v48
	v_sub_f32_e32 v135, v135, v48
	v_sub_f32_e32 v134, v134, v48
	v_sub_f32_e32 v133, v133, v48
	v_sub_f32_e32 v132, v132, v48
	v_mov_b32_e32 v121, v120
	v_mov_b32_e32 v122, v120
	v_mov_b32_e32 v123, v120
	v_sub_f32_e32 v144, v144, v49
	v_sub_f32_e32 v145, v145, v49
	v_sub_f32_e32 v146, v146, v49
	v_sub_f32_e32 v147, v147, v49
	v_sub_f32_e32 v172, v172, v49
	v_sub_f32_e32 v173, v173, v49
	v_sub_f32_e32 v174, v174, v49
	v_sub_f32_e32 v175, v175, v49
	v_sub_f32_e32 v143, v143, v49
	v_sub_f32_e32 v142, v142, v49
	v_sub_f32_e32 v141, v141, v49
	v_sub_f32_e32 v140, v140, v49
	v_sub_f32_e32 v131, v131, v49
	v_sub_f32_e32 v130, v130, v49
	v_sub_f32_e32 v129, v129, v49
	v_sub_f32_e32 v128, v128, v49
	v_mov_b32_e32 v125, v124
	v_mov_b32_e32 v126, v124
	v_mov_b32_e32 v127, v124
	v_mov_b32_e32 v48, v120
	v_mov_b32_e32 v49, v120
	v_mov_b32_e32 v50, v120
	v_mov_b32_e32 v51, v120
	v_mov_b32_e32 v52, v124
	v_mov_b32_e32 v53, v124
	v_mov_b32_e32 v54, v124
	v_mov_b32_e32 v55, v124
	s_branch .LBB0_974
